# v_k3 + phase_rows: gamma/beta and modulation chunk loads issued together with the row loads (3 row-phase copies), counted waits
# speedup vs baseline: 1.0040x; 1.0026x over previous
; DI float wave_sum(float v) { return xsum32(xsum16(allreduce16(v))); }
; DI void phase_rows(const Params& p, int mode, int half) {
;     ...
;   for (int rr = gw; rr < nrows; rr += nw) {
;     int m = (mode == 0) ? rr : half * MH + rr;
;     int b = m / T, t = m % T;
;     if (mode == 2 && t < 256) continue;
;     const float* src = (mode == 0) ? xrow(p, 0, b, t) : p.hbuf + (long)rr * DM;
;     float v[16];
; #pragma unroll
;     for (int q = 0; q < 4; q++) {
;       f32x4v x4 = *(const f32x4v*)(src + q * 256 + lane * 4);
;       v[q * 4] = x4.x; v[q * 4 + 1] = x4.y; v[q * 4 + 2] = x4.z; v[q * 4 + 3] = x4.w;
;     }
;     ...
;     if (mode <= 1) {
;       int l = mode;
;       float s = 0.f;
; #pragma unroll
;       for (int i = 0; i < 16; i++) s += v[i];
;       float mu = wave_sum(s) * (1.f / 1024.f);
;       float s2 = 0.f;
; #pragma unroll
;       for (int i = 0; i < 16; i++) { float d = v[i] - mu; s2 += d * d; }
;       float rs = rsqrtf(wave_sum(s2) * (1.f / 1024.f) + 1e-6f);
;       const float* md = p.mod + ((long)l * 9 + (t < 256 ? 8 : b)) * 3072;
;       u16* dst = p.A + (long)m * DM;
; #pragma unroll
;       for (int q = 0; q < 4; q++) {
;         int c = q * 256 + lane * 4;
;         f32x4v sh4 = *(const f32x4v*)(md + c), sc4 = *(const f32x4v*)(md + 1024 + c);
.LBB0_26:
	v_mul_hi_i32 v7, v0, s3
	s_waitcnt vmcnt(0)
	v_lshrrev_b32_e32 v12, 31, v7
	v_ashrrev_i32_e32 v7, 11, v7
	v_ashrrev_i32_e32 v1, 31, v0
	v_add_u32_e32 v12, v7, v12
	v_lshlrev_b64 v[10:11], 11, v[0:1]
	v_mul_i32_i24_e32 v1, 0x1100, v12
	v_sub_u32_e32 v1, v0, v1
	v_mov_b32_e32 v9, s5
	v_mov_b32_e32 v14, s9
	v_mov_b32_e32 v15, s4
	v_mov_b32_e32 v16, s8
	v_ashrrev_i32_e32 v7, 31, v1
	v_add_u32_e32 v17, 0xffffff00, v1
	v_cmp_gt_i32_e32 vcc, s68, v1
	v_lshl_add_u64 v[34:35], v[2:3], 0, v[10:11]
	v_ashrrev_i32_e32 v13, 31, v12
	v_cndmask_b32_e32 v11, v9, v14, vcc
	v_cndmask_b32_e32 v10, v15, v16, vcc
	v_cndmask_b32_e32 v15, 0, v7, vcc
	v_cndmask_b32_e32 v14, v17, v1, vcc
	v_cndmask_b32_e64 v1, 24, 20, vcc
	v_cndmask_b32_e64 v7, v12, 8, vcc
	v_lshlrev_b64 v[12:13], v1, v[12:13]
	v_mul_hi_i32_i24_e32 v17, 0x3000, v7
	v_mul_i32_i24_e32 v16, 0x3000, v7
	v_lshlrev_b64 v[14:15], 12, v[14:15]
	v_lshl_add_u64 v[10:11], v[10:11], 0, v[12:13]
	v_lshl_add_u64 v[12:13], s[46:47], 0, v[16:17]
	v_lshl_add_u64 v[10:11], v[10:11], 0, v[14:15]
	v_lshl_add_u64 v[36:37], v[12:13], 0, s[38:39]
	v_lshl_add_u64 v[38:39], v[12:13], 0, v[176:177]
	v_lshl_add_u64 v[26:27], v[10:11], 0, v[176:177]
	v_lshl_add_u64 v[30:31], v[36:37], 0, v[176:177]
	global_load_dwordx4 v[10:13], v[38:39], off
	global_load_dwordx4 v[14:17], v[26:27], off
	global_load_dwordx4 v[18:21], v[26:27], off offset:1024
	global_load_dwordx4 v[22:25], v[26:27], off offset:2048
	s_nop 0
	global_load_dwordx4 v[26:29], v[26:27], off offset:3072
	s_nop 0
	global_load_dwordx4 v[222:225], v[30:31], off offset:1024
	global_load_dwordx4 v[230:233], v[30:31], off offset:2048
	global_load_dwordx4 v[238:241], v[30:31], off offset:3072
	global_load_dwordx4 v[30:33], v[30:31], off
	global_load_dwordx4 v[226:229], v[38:39], off offset:1024
	global_load_dwordx4 v[234:237], v[38:39], off offset:2048
	global_load_dwordx4 v[242:245], v[38:39], off offset:3072
	v_mov_b32_e32 v5, v177
	v_lshl_add_u64 v[40:41], v[36:37], 0, v[4:5]
	v_mov_b32_e32 v7, v177
	v_mov_b32_e32 v9, v177
	v_add_u32_e32 v0, s12, v0
	s_mov_b32 s13, 0x87ff
	s_waitcnt vmcnt(10)
	v_add_f32_e32 v1, 0, v14
	v_add_f32_e32 v1, v15, v1
	v_add_f32_e32 v1, v16, v1
	v_add_f32_e32 v1, v17, v1
	s_waitcnt vmcnt(9)
	v_add_f32_e32 v1, v18, v1
	v_add_f32_e32 v1, v19, v1
	v_add_f32_e32 v1, v20, v1
	v_add_f32_e32 v1, v21, v1
	s_waitcnt vmcnt(8)
	v_add_f32_e32 v1, v22, v1
	v_add_f32_e32 v1, v23, v1
	v_add_f32_e32 v1, v24, v1
	v_add_f32_e32 v1, v25, v1
	s_waitcnt vmcnt(7)
	v_add_f32_e32 v1, v26, v1
	v_add_f32_e32 v1, v27, v1
	v_add_f32_e32 v1, v28, v1
	v_add_f32_e32 v1, v29, v1
	s_waitcnt vmcnt(3)
; DI float wave_sum(float v) { return xsum32(xsum16(allreduce16(v))); }
; DI void phase_rows(const Params& p, int mode, int half) {
;     ...
;       int l = mode;
;       float s = 0.f;
; #pragma unroll
;       for (int i = 0; i < 16; i++) s += v[i];
;       float mu = wave_sum(s) * (1.f / 1024.f);
;       float s2 = 0.f;
; #pragma unroll
;       for (int i = 0; i < 16; i++) { float d = v[i] - mu; s2 += d * d; }
;       float rs = rsqrtf(wave_sum(s2) * (1.f / 1024.f) + 1e-6f);
;       const float* md = p.mod + ((long)l * 9 + (t < 256 ? 8 : b)) * 3072;
;       u16* dst = p.A + (long)m * DM;
; #pragma unroll
;       for (int q = 0; q < 4; q++) {
;         int c = q * 256 + lane * 4;
;         f32x4v sh4 = *(const f32x4v*)(md + c), sc4 = *(const f32x4v*)(md + 1024 + c);
;         float a0 = (v[q * 4] - mu) * rs * (1.f + sc4.x) + sh4.x;
;         float a1 = (v[q * 4 + 1] - mu) * rs * (1.f + sc4.y) + sh4.y;
;         float a2 = (v[q * 4 + 2] - mu) * rs * (1.f + sc4.z) + sh4.z;
;         float a3 = (v[q * 4 + 3] - mu) * rs * (1.f + sc4.w) + sh4.w;
;         u32x2 o2; o2.x = pack2(a0, a1); o2.y = pack2(a2, a3);
;         *(u32x2*)(dst + c) = o2;
;       }
	v_pk_add_f32 v[30:31], v[30:31], 1.0 op_sel_hi:[1, 0]
	v_pk_add_f32 v[32:33], v[32:33], 1.0 op_sel_hi:[1, 0]
	v_add_f32_dpp v1, v1, v1 quad_perm:[1, 0, 3, 2] row_mask:0xf bank_mask:0xf bound_ctrl:1
	s_nop 1
	v_add_f32_dpp v1, v1, v1 quad_perm:[2, 3, 0, 1] row_mask:0xf bank_mask:0xf bound_ctrl:1
	s_nop 1
	v_add_f32_dpp v1, v1, v1 row_half_mirror row_mask:0xf bank_mask:0xf bound_ctrl:1
	s_nop 1
	v_add_f32_dpp v1, v1, v1 row_mirror row_mask:0xf bank_mask:0xf bound_ctrl:1
	v_mov_b32_e32 v5, v1
	s_nop 1
	v_permlane16_swap_b32_e32 v1, v5
	v_add_f32_e32 v1, v1, v5
	v_mov_b32_e32 v5, v1
	s_nop 1
	v_permlane32_swap_b32_e32 v1, v5
	v_add_f32_e32 v1, v1, v5
	v_mul_f32_e32 v42, 0x3a800000, v1
	v_pk_add_f32 v[14:15], v[14:15], v[42:43] op_sel_hi:[1, 0] neg_lo:[0, 1] neg_hi:[0, 1]
	v_pk_add_f32 v[16:17], v[16:17], v[42:43] op_sel_hi:[1, 0] neg_lo:[0, 1] neg_hi:[0, 1]
	v_pk_mul_f32 v[44:45], v[14:15], v[14:15]
	v_pk_add_f32 v[20:21], v[20:21], v[42:43] op_sel_hi:[1, 0] neg_lo:[0, 1] neg_hi:[0, 1]
	v_pk_add_f32 v[18:19], v[18:19], v[42:43] op_sel_hi:[1, 0] neg_lo:[0, 1] neg_hi:[0, 1]
	v_pk_add_f32 v[24:25], v[24:25], v[42:43] op_sel_hi:[1, 0] neg_lo:[0, 1] neg_hi:[0, 1]
	v_pk_add_f32 v[22:23], v[22:23], v[42:43] op_sel_hi:[1, 0] neg_lo:[0, 1] neg_hi:[0, 1]
	v_pk_add_f32 v[28:29], v[28:29], v[42:43] op_sel_hi:[1, 0] neg_lo:[0, 1] neg_hi:[0, 1]
	v_pk_add_f32 v[26:27], v[26:27], v[42:43] op_sel_hi:[1, 0] neg_lo:[0, 1] neg_hi:[0, 1]
	v_pk_mul_f32 v[42:43], v[16:17], v[16:17]
	v_add_f32_e32 v1, v44, v45
	v_add_f32_e32 v1, v42, v1
	v_pk_mul_f32 v[48:49], v[18:19], v[18:19]
	v_add_f32_e32 v1, v43, v1
	v_add_f32_e32 v1, v48, v1
	v_pk_mul_f32 v[46:47], v[20:21], v[20:21]
	v_add_f32_e32 v1, v49, v1
	v_add_f32_e32 v1, v46, v1
	v_pk_mul_f32 v[52:53], v[22:23], v[22:23]
	v_add_f32_e32 v1, v47, v1
	v_add_f32_e32 v1, v52, v1
	v_pk_mul_f32 v[50:51], v[24:25], v[24:25]
	v_add_f32_e32 v1, v53, v1
	v_add_f32_e32 v1, v50, v1
	v_pk_mul_f32 v[56:57], v[26:27], v[26:27]
	v_add_f32_e32 v1, v51, v1
	v_add_f32_e32 v1, v56, v1
	v_pk_mul_f32 v[54:55], v[28:29], v[28:29]
	v_add_f32_e32 v1, v57, v1
	v_add_f32_e32 v1, v54, v1
	v_add_f32_e32 v1, v55, v1
	s_nop 1
	v_add_f32_dpp v1, v1, v1 quad_perm:[1, 0, 3, 2] row_mask:0xf bank_mask:0xf bound_ctrl:1
	s_nop 1
	v_add_f32_dpp v1, v1, v1 quad_perm:[2, 3, 0, 1] row_mask:0xf bank_mask:0xf bound_ctrl:1
	s_nop 1
	v_add_f32_dpp v1, v1, v1 row_half_mirror row_mask:0xf bank_mask:0xf bound_ctrl:1
	s_nop 1
	v_add_f32_dpp v1, v1, v1 row_mirror row_mask:0xf bank_mask:0xf bound_ctrl:1
	v_mov_b32_e32 v5, v1
	s_nop 1
	v_permlane16_swap_b32_e32 v1, v5
	v_add_f32_e32 v1, v1, v5
	v_mov_b32_e32 v5, v1
	s_nop 1
	v_permlane32_swap_b32_e32 v1, v5
	v_add_f32_e32 v1, v1, v5
	v_fmamk_f32 v1, v1, 0x3a800000, v199
	v_mul_f32_e32 v5, 0x4b800000, v1
	v_cmp_gt_f32_e32 vcc, s21, v1
	s_nop 1
	v_cndmask_b32_e32 v1, v1, v5, vcc
	v_rsq_f32_e32 v1, v1
	s_nop 0
	v_mul_f32_e32 v5, 0x45800000, v1
	v_cndmask_b32_e32 v42, v1, v5, vcc
	v_pk_mul_f32 v[14:15], v[14:15], v[42:43] op_sel_hi:[1, 0]
	v_pk_mul_f32 v[16:17], v[16:17], v[42:43] op_sel_hi:[1, 0]
	v_pk_fma_f32 v[10:11], v[30:31], v[14:15], v[10:11]
	v_pk_fma_f32 v[12:13], v[32:33], v[16:17], v[12:13]
	v_cvt_pk_bf16_f32 v10, v10, v11
	v_cvt_pk_bf16_f32 v11, v12, v13
	global_store_dwordx2 v[34:35], v[10:11], off
	s_nop 0
	s_nop 0
	s_nop 0
	v_pk_mul_f32 v[18:19], v[18:19], v[42:43] op_sel_hi:[1, 0]
	v_pk_mul_f32 v[20:21], v[20:21], v[42:43] op_sel_hi:[1, 0]
	v_lshl_add_u64 v[30:31], v[36:37], 0, v[6:7]
	v_cmp_lt_i32_e32 vcc, s13, v0
	s_or_b64 s[36:37], vcc, s[36:37]
	s_waitcnt vmcnt(4)
	v_pk_add_f32 v[10:11], v[222:223], 1.0 op_sel_hi:[1, 0]
	v_pk_add_f32 v[12:13], v[224:225], 1.0 op_sel_hi:[1, 0]
	s_waitcnt vmcnt(3)
	v_pk_fma_f32 v[10:11], v[10:11], v[18:19], v[226:227]
	v_pk_fma_f32 v[12:13], v[12:13], v[20:21], v[228:229]
	v_cvt_pk_bf16_f32 v10, v10, v11
	v_cvt_pk_bf16_f32 v11, v12, v13
	global_store_dwordx2 v[34:35], v[10:11], off offset:512
	s_nop 0
	s_nop 0
	s_nop 0
	v_pk_mul_f32 v[20:21], v[22:23], v[42:43] op_sel_hi:[1, 0]
	v_pk_mul_f32 v[22:23], v[24:25], v[42:43] op_sel_hi:[1, 0]
	v_lshl_add_u64 v[18:19], v[36:37], 0, v[8:9]
	s_waitcnt vmcnt(4)
	v_pk_add_f32 v[10:11], v[230:231], 1.0 op_sel_hi:[1, 0]
	v_pk_add_f32 v[12:13], v[232:233], 1.0 op_sel_hi:[1, 0]
	s_waitcnt vmcnt(3)
	v_pk_fma_f32 v[10:11], v[10:11], v[20:21], v[234:235]
	v_pk_fma_f32 v[12:13], v[12:13], v[22:23], v[236:237]
	v_cvt_pk_bf16_f32 v10, v10, v11
	v_cvt_pk_bf16_f32 v11, v12, v13
	global_store_dwordx2 v[34:35], v[10:11], off offset:1024
	s_nop 0
	s_nop 0
	s_nop 0
	v_pk_mul_f32 v[18:19], v[26:27], v[42:43] op_sel_hi:[1, 0]
	v_pk_mul_f32 v[20:21], v[28:29], v[42:43] op_sel_hi:[1, 0]
	s_waitcnt vmcnt(4)
	v_pk_add_f32 v[10:11], v[238:239], 1.0 op_sel_hi:[1, 0]
	v_pk_add_f32 v[12:13], v[240:241], 1.0 op_sel_hi:[1, 0]
	s_waitcnt vmcnt(3)
	v_pk_fma_f32 v[10:11], v[18:19], v[10:11], v[242:243]
	v_pk_fma_f32 v[12:13], v[20:21], v[12:13], v[244:245]
	v_cvt_pk_bf16_f32 v10, v10, v11
	v_cvt_pk_bf16_f32 v11, v12, v13
	global_store_dwordx2 v[34:35], v[10:11], off offset:1536
	s_andn2_b64 exec, exec, s[36:37]
	s_cbranch_execnz .LBB0_26

; DI float wave_sum(float v) { return xsum32(xsum16(allreduce16(v))); }
; DI void phase_rows(const Params& p, int mode, int half) {
;     ...
;     const float* src = (mode == 0) ? xrow(p, 0, b, t) : p.hbuf + (long)rr * DM;
;     float v[16];
; #pragma unroll
;     for (int q = 0; q < 4; q++) {
;       f32x4v x4 = *(const f32x4v*)(src + q * 256 + lane * 4);
;       v[q * 4] = x4.x; v[q * 4 + 1] = x4.y; v[q * 4 + 2] = x4.z; v[q * 4 + 3] = x4.w;
;     }
;     if (mode >= 1) {
;       int l = mode - 1;
;       float s = 0.f;
; #pragma unroll
;       for (int i = 0; i < 16; i++) s += v[i];
;       float mu = wave_sum(s) * (1.f / 1024.f);
;       float s2 = 0.f;
; #pragma unroll
;       for (int i = 0; i < 16; i++) { float d = v[i] - mu; s2 += d * d; }
;       float rs = rsqrtf(wave_sum(s2) * (1.f / 1024.f) + 1e-5f);
;       const float* g = p.in[28] + l * 1024;
;       const float* bb = p.in[29] + l * 1024;
;       float* dst = (mode == 2) ? p.out + ((long)b * 4096 + (t - 256)) * DM
.LBB0_950:
	v_lshlrev_b64 v[0:1], 12, v[0:1]
	v_lshl_add_u64 v[0:1], v[2:3], 0, v[0:1]
	v_lshlrev_b32_e32 v176, 2, v18
	s_waitcnt vmcnt(0)
	v_lshl_add_u64 v[12:13], v[0:1], 0, v[176:177]
	global_load_dwordx4 v[0:3], v[12:13], off
	global_load_dwordx4 v[4:7], v[12:13], off offset:1024
	global_load_dwordx4 v[8:11], v[12:13], off offset:2048
	s_nop 0
	global_load_dwordx4 v[12:15], v[12:13], off offset:3072
	s_andn2_b64 vcc, exec, s[44:45]
	s_cbranch_vccnz .LBB0_960
	global_load_dwordx4 v[222:225], v[20:21], off
	global_load_dwordx4 v[226:229], v[22:23], off
	global_load_dwordx4 v[230:233], v[20:21], off offset:1024
	global_load_dwordx4 v[234:237], v[22:23], off offset:1024
	global_load_dwordx4 v[238:241], v[20:21], off offset:2048
	global_load_dwordx4 v[242:245], v[22:23], off offset:2048
	global_load_dwordx4 v[246:249], v[20:21], off offset:3072
	s_waitcnt vmcnt(10)
	v_add_f32_e32 v27, 0, v0
	v_add_f32_e32 v27, v1, v27
	v_add_f32_e32 v27, v2, v27
	v_add_f32_e32 v27, v3, v27
	s_waitcnt vmcnt(9)
	v_add_f32_e32 v27, v4, v27
	v_add_f32_e32 v27, v5, v27
	v_add_f32_e32 v27, v6, v27
	v_add_f32_e32 v27, v7, v27
	s_waitcnt vmcnt(8)
	v_add_f32_e32 v27, v8, v27
	v_add_f32_e32 v27, v9, v27
	v_add_f32_e32 v27, v10, v27
	v_add_f32_e32 v27, v11, v27
	s_waitcnt vmcnt(7)
	v_add_f32_e32 v27, v12, v27
	v_add_f32_e32 v27, v13, v27
	v_add_f32_e32 v27, v14, v27
	v_add_f32_e32 v27, v15, v27
	v_readlane_b32 s72, v252, 38
	v_readlane_b32 s84, v252, 50
	v_add_f32_dpp v27, v27, v27 quad_perm:[1, 0, 3, 2] row_mask:0xf bank_mask:0xf bound_ctrl:1
	v_readlane_b32 s85, v252, 51
	s_mov_b64 s[56:57], -1
	v_add_f32_dpp v27, v27, v27 quad_perm:[2, 3, 0, 1] row_mask:0xf bank_mask:0xf bound_ctrl:1
	s_and_b64 vcc, exec, s[42:43]
	v_readlane_b32 s73, v252, 39
	v_add_f32_dpp v27, v27, v27 row_half_mirror row_mask:0xf bank_mask:0xf bound_ctrl:1
	v_readlane_b32 s74, v252, 40
	v_readlane_b32 s75, v252, 41
	v_add_f32_dpp v27, v27, v27 row_mirror row_mask:0xf bank_mask:0xf bound_ctrl:1
	v_mov_b32_e32 v29, v27
	s_nop 1
	v_permlane16_swap_b32_e32 v27, v29
	v_add_f32_e32 v27, v27, v29
	v_mov_b32_e32 v29, v27
	s_nop 1
	v_permlane32_swap_b32_e32 v27, v29
	v_add_f32_e32 v27, v27, v29
	v_mul_f32_e32 v38, 0x3a800000, v27
	v_pk_add_f32 v[0:1], v[0:1], v[38:39] op_sel_hi:[1, 0] neg_lo:[0, 1] neg_hi:[0, 1]
	v_pk_add_f32 v[2:3], v[2:3], v[38:39] op_sel_hi:[1, 0] neg_lo:[0, 1] neg_hi:[0, 1]
	v_pk_mul_f32 v[40:41], v[0:1], v[0:1]
	v_pk_mul_f32 v[42:43], v[2:3], v[2:3]
	v_add_f32_e32 v27, v40, v41
	v_pk_add_f32 v[4:5], v[4:5], v[38:39] op_sel_hi:[1, 0] neg_lo:[0, 1] neg_hi:[0, 1]
	v_add_f32_e32 v27, v42, v27
	v_pk_mul_f32 v[44:45], v[4:5], v[4:5]
	v_add_f32_e32 v27, v43, v27
	v_pk_add_f32 v[6:7], v[6:7], v[38:39] op_sel_hi:[1, 0] neg_lo:[0, 1] neg_hi:[0, 1]
	v_add_f32_e32 v27, v44, v27
	v_pk_mul_f32 v[46:47], v[6:7], v[6:7]
	v_add_f32_e32 v27, v45, v27
	v_pk_add_f32 v[8:9], v[8:9], v[38:39] op_sel_hi:[1, 0] neg_lo:[0, 1] neg_hi:[0, 1]
	v_add_f32_e32 v27, v46, v27
	v_pk_mul_f32 v[48:49], v[8:9], v[8:9]
	v_add_f32_e32 v27, v47, v27
	v_pk_add_f32 v[10:11], v[10:11], v[38:39] op_sel_hi:[1, 0] neg_lo:[0, 1] neg_hi:[0, 1]
	v_add_f32_e32 v27, v48, v27
	v_pk_mul_f32 v[50:51], v[10:11], v[10:11]
	v_add_f32_e32 v27, v49, v27
	v_pk_add_f32 v[12:13], v[12:13], v[38:39] op_sel_hi:[1, 0] neg_lo:[0, 1] neg_hi:[0, 1]
	v_add_f32_e32 v27, v50, v27
	v_pk_mul_f32 v[52:53], v[12:13], v[12:13]
	v_add_f32_e32 v27, v51, v27
	v_pk_add_f32 v[14:15], v[14:15], v[38:39] op_sel_hi:[1, 0] neg_lo:[0, 1] neg_hi:[0, 1]
	v_add_f32_e32 v27, v52, v27
	v_pk_mul_f32 v[38:39], v[14:15], v[14:15]
	v_add_f32_e32 v27, v53, v27
	v_add_f32_e32 v27, v38, v27
	v_add_f32_e32 v27, v39, v27
	v_mov_b64_e32 v[40:41], s[84:85]
	v_readlane_b32 s76, v252, 42
	v_add_f32_dpp v27, v27, v27 quad_perm:[1, 0, 3, 2] row_mask:0xf bank_mask:0xf bound_ctrl:1
	v_readlane_b32 s77, v252, 43
	v_readlane_b32 s78, v252, 44
	v_add_f32_dpp v27, v27, v27 quad_perm:[2, 3, 0, 1] row_mask:0xf bank_mask:0xf bound_ctrl:1
	v_readlane_b32 s79, v252, 45
	v_readlane_b32 s80, v252, 46
	v_add_f32_dpp v27, v27, v27 row_half_mirror row_mask:0xf bank_mask:0xf bound_ctrl:1
	v_readlane_b32 s81, v252, 47
	v_readlane_b32 s82, v252, 48
	v_add_f32_dpp v27, v27, v27 row_mirror row_mask:0xf bank_mask:0xf bound_ctrl:1
	v_mov_b32_e32 v29, v27
	s_nop 1
	v_permlane16_swap_b32_e32 v27, v29
	v_add_f32_e32 v27, v27, v29
	v_mov_b32_e32 v29, v27
	s_nop 1
	v_permlane32_swap_b32_e32 v27, v29
	v_readlane_b32 s83, v252, 49
	v_readlane_b32 s86, v252, 52
	v_readlane_b32 s87, v252, 53
	s_cbranch_vccz .LBB0_957
	v_readlane_b32 s72, v255, 1
	v_readlane_b32 s80, v255, 9
	v_readlane_b32 s81, v255, 10
	v_readlane_b32 s73, v255, 2
	v_readlane_b32 s74, v255, 3
	v_mov_b64_e32 v[40:41], s[80:81]
	v_readlane_b32 s75, v255, 4
	v_readlane_b32 s76, v255, 5
	v_readlane_b32 s77, v255, 6
	v_readlane_b32 s78, v255, 7
	v_readlane_b32 s79, v255, 8
	v_readlane_b32 s82, v255, 11
	v_readlane_b32 s83, v255, 12
	v_readlane_b32 s84, v255, 13
	v_readlane_b32 s85, v255, 14
	v_readlane_b32 s86, v255, 15
	v_readlane_b32 s87, v255, 16
	s_and_saveexec_b64 s[56:57], s[0:1]
	s_xor_b64 s[0:1], exec, s[56:57]
	s_cbranch_execz .LBB0_954
	v_readlane_b32 s72, v252, 38
	v_readlane_b32 s84, v252, 50
	v_readlane_b32 s85, v252, 51
	v_add_u32_e32 v38, 0xffffff00, v36
	v_mov_b32_e32 v39, v177
	v_readlane_b32 s73, v252, 39
	v_readlane_b32 s74, v252, 40
	v_readlane_b32 s75, v252, 41
	v_readlane_b32 s76, v252, 42
	v_readlane_b32 s77, v252, 43
	v_readlane_b32 s78, v252, 44
	v_readlane_b32 s79, v252, 45
	v_readlane_b32 s80, v252, 46
	v_readlane_b32 s81, v252, 47
	v_readlane_b32 s82, v252, 48
	v_readlane_b32 s83, v252, 49
	v_readlane_b32 s86, v252, 52
	v_readlane_b32 s87, v252, 53
	v_mov_b64_e32 v[40:41], s[84:85]

; DI float wave_sum(float v) { return xsum32(xsum16(allreduce16(v))); }
; DI void phase_rows(const Params& p, int mode, int half) {
;     ...
;       float* dst = (mode == 2) ? p.out + ((long)b * 4096 + (t - 256)) * DM
;                                : (t < 256 ? p.ctx1 + ((long)b * 256 + t) * DM : p.out + ((long)b * 4096 + (t - 256)) * DM);
; #pragma unroll
;       for (int q = 0; q < 4; q++) {
;         int c = q * 256 + lane * 4;
;         f32x4v g4 = *(const f32x4v*)(g + c), b4 = *(const f32x4v*)(bb + c);
;         v[q * 4] = (v[q * 4] - mu) * rs * g4.x + b4.x;
;         v[q * 4 + 1] = (v[q * 4 + 1] - mu) * rs * g4.y + b4.y;
;         v[q * 4 + 2] = (v[q * 4 + 2] - mu) * rs * g4.z + b4.z;
;         v[q * 4 + 3] = (v[q * 4 + 3] - mu) * rs * g4.w + b4.w;
;         *(f32x4v*)(dst + c) = f32x4v{v[q * 4], v[q * 4 + 1], v[q * 4 + 2], v[q * 4 + 3]};
;       }
;     }
;     if (mode <= 1) {
;       int l = mode;
;       float s = 0.f;
; #pragma unroll
;       for (int i = 0; i < 16; i++) s += v[i];
;       float mu = wave_sum(s) * (1.f / 1024.f);
;       float s2 = 0.f;
; #pragma unroll
;       for (int i = 0; i < 16; i++) { float d = v[i] - mu; s2 += d * d; }
;       float rs = rsqrtf(wave_sum(s2) * (1.f / 1024.f) + 1e-6f);
;       const float* md = p.mod + ((long)l * 9 + (t < 256 ? 8 : b)) * 3072;
;       u16* dst = p.A + (long)m * DM;
; #pragma unroll
;       for (int q = 0; q < 4; q++) {
;         int c = q * 256 + lane * 4;
;         f32x4v sh4 = *(const f32x4v*)(md + c), sc4 = *(const f32x4v*)(md + 1024 + c);
.LBB0_959:
	v_lshlrev_b64 v[36:37], v42, v[34:35]
	v_lshl_add_u64 v[36:37], v[40:41], 0, v[36:37]
	v_lshlrev_b64 v[38:39], 12, v[38:39]
	v_lshl_add_u64 v[46:47], v[36:37], 0, v[38:39]
	global_load_dwordx4 v[40:43], v[22:23], off offset:3072
	s_nop 0
	s_nop 0
	v_add_f32_e32 v27, v27, v29
	v_fmamk_f32 v27, v27, 0x3a800000, v201
	s_mov_b32 s0, 0x800000
	v_cmp_gt_f32_e32 vcc, s0, v27
	v_mul_f32_e32 v29, 0x4b800000, v27
	v_lshl_add_u64 v[46:47], v[46:47], 0, v[176:177]
	v_cndmask_b32_e32 v27, v27, v29, vcc
	v_rsq_f32_e32 v27, v27
	s_nop 0
	v_mul_f32_e32 v29, 0x45800000, v27
	v_cndmask_b32_e32 v44, v27, v29, vcc
	v_pk_mul_f32 v[0:1], v[0:1], v[44:45] op_sel_hi:[1, 0]
	v_pk_mul_f32 v[2:3], v[2:3], v[44:45] op_sel_hi:[1, 0]
	v_pk_mul_f32 v[4:5], v[4:5], v[44:45] op_sel_hi:[1, 0]
	v_pk_mul_f32 v[6:7], v[6:7], v[44:45] op_sel_hi:[1, 0]
	v_pk_mul_f32 v[8:9], v[8:9], v[44:45] op_sel_hi:[1, 0]
	v_pk_mul_f32 v[10:11], v[10:11], v[44:45] op_sel_hi:[1, 0]
	v_pk_mul_f32 v[12:13], v[12:13], v[44:45] op_sel_hi:[1, 0]
	v_pk_mul_f32 v[14:15], v[14:15], v[44:45] op_sel_hi:[1, 0]
	s_waitcnt vmcnt(6)
	v_pk_fma_f32 v[0:1], v[0:1], v[222:223], v[226:227]
	v_pk_fma_f32 v[2:3], v[2:3], v[224:225], v[228:229]
	global_store_dwordx4 v[46:47], v[0:3], off
	s_nop 0
	s_nop 0
	s_waitcnt vmcnt(5)
	v_pk_fma_f32 v[4:5], v[4:5], v[230:231], v[234:235]
	v_pk_fma_f32 v[6:7], v[6:7], v[232:233], v[236:237]
	global_store_dwordx4 v[46:47], v[4:7], off offset:1024
	s_nop 0
	s_nop 0
	s_waitcnt vmcnt(4)
	v_pk_fma_f32 v[8:9], v[8:9], v[238:239], v[242:243]
	v_pk_fma_f32 v[10:11], v[10:11], v[240:241], v[244:245]
	global_store_dwordx4 v[46:47], v[8:11], off offset:2048
	s_nop 0
	s_nop 0
	s_waitcnt vmcnt(3)
	v_pk_fma_f32 v[12:13], v[12:13], v[246:247], v[40:41]
	v_pk_fma_f32 v[14:15], v[14:15], v[248:249], v[42:43]
	global_store_dwordx4 v[46:47], v[12:15], off offset:3072
.LBB0_960:
	s_andn2_b64 vcc, exec, s[46:47]
	s_cbranch_vccnz .LBB0_944
	v_cndmask_b32_e64 v34, v34, 8, s[36:37]
	v_readlane_b32 s72, v254, 35
	v_ashrrev_i32_e32 v35, 31, v34
	v_readlane_b32 s82, v254, 45
	v_readlane_b32 s83, v254, 46
	v_lshl_add_u64 v[34:35], s[48:49], 0, v[34:35]
	s_waitcnt vmcnt(3)
	v_add_f32_e32 v27, 0, v0
	v_mov_b64_e32 v[36:37], s[82:83]
	v_mad_u64_u32 v[38:39], s[0:1], v34, s33, v[36:37]
	v_mov_b32_e32 v34, v39
	v_mad_u64_u32 v[34:35], s[0:1], v35, s33, v[34:35]
	v_mov_b32_e32 v39, v34
	s_mov_b64 s[0:1], 0x1000
	v_lshl_add_u64 v[42:43], v[38:39], 0, s[0:1]
	v_lshl_add_u64 v[34:35], v[42:43], 0, v[176:177]
	global_load_dwordx4 v[222:225], v[34:35], off offset:1024
	global_load_dwordx4 v[230:233], v[34:35], off offset:2048
	global_load_dwordx4 v[238:241], v[34:35], off offset:3072
	global_load_dwordx4 v[34:37], v[34:35], off
	v_lshl_add_u64 v[44:45], v[38:39], 0, v[176:177]
	global_load_dwordx4 v[38:41], v[44:45], off
	global_load_dwordx4 v[226:229], v[44:45], off offset:1024
	global_load_dwordx4 v[234:237], v[44:45], off offset:2048
	global_load_dwordx4 v[242:245], v[44:45], off offset:3072
	v_add_f32_e32 v27, v1, v27
	v_add_f32_e32 v27, v2, v27
	v_add_f32_e32 v27, v3, v27
	s_waitcnt vmcnt(10)
	v_add_f32_e32 v27, v4, v27
	v_add_f32_e32 v27, v5, v27
	v_add_f32_e32 v27, v6, v27
	v_add_f32_e32 v27, v7, v27
	s_waitcnt vmcnt(9)
	v_add_f32_e32 v27, v8, v27
	v_add_f32_e32 v27, v9, v27
	v_add_f32_e32 v27, v10, v27
	v_add_f32_e32 v27, v11, v27
	s_waitcnt vmcnt(8)
; DI float wave_sum(float v) { return xsum32(xsum16(allreduce16(v))); }
; DI void phase_rows(const Params& p, int mode, int half) {
;     ...
;     if (mode <= 1) {
;       int l = mode;
;       float s = 0.f;
; #pragma unroll
;       for (int i = 0; i < 16; i++) s += v[i];
;       float mu = wave_sum(s) * (1.f / 1024.f);
;       float s2 = 0.f;
; #pragma unroll
;       for (int i = 0; i < 16; i++) { float d = v[i] - mu; s2 += d * d; }
;       float rs = rsqrtf(wave_sum(s2) * (1.f / 1024.f) + 1e-6f);
;       const float* md = p.mod + ((long)l * 9 + (t < 256 ? 8 : b)) * 3072;
;       u16* dst = p.A + (long)m * DM;
; #pragma unroll
;       for (int q = 0; q < 4; q++) {
;         int c = q * 256 + lane * 4;
;         f32x4v sh4 = *(const f32x4v*)(md + c), sc4 = *(const f32x4v*)(md + 1024 + c);
;         float a0 = (v[q * 4] - mu) * rs * (1.f + sc4.x) + sh4.x;
;         float a1 = (v[q * 4 + 1] - mu) * rs * (1.f + sc4.y) + sh4.y;
;         float a2 = (v[q * 4 + 2] - mu) * rs * (1.f + sc4.z) + sh4.z;
;         float a3 = (v[q * 4 + 3] - mu) * rs * (1.f + sc4.w) + sh4.w;
;         u32x2 o2; o2.x = pack2(a0, a1); o2.y = pack2(a2, a3);
;         *(u32x2*)(dst + c) = o2;
;       }
;     }
	v_add_f32_e32 v27, v12, v27
	v_add_f32_e32 v27, v13, v27
	v_add_f32_e32 v27, v14, v27
	v_add_f32_e32 v27, v15, v27
	s_mov_b32 s0, 0x800000
	v_ashrrev_i32_e32 v33, 31, v32
	v_add_f32_dpp v27, v27, v27 quad_perm:[1, 0, 3, 2] row_mask:0xf bank_mask:0xf bound_ctrl:1
	v_lshlrev_b64 v[32:33], 11, v[32:33]
	v_lshl_add_u64 v[32:33], v[24:25], 0, v[32:33]
	v_add_f32_dpp v27, v27, v27 quad_perm:[2, 3, 0, 1] row_mask:0xf bank_mask:0xf bound_ctrl:1
	v_mov_b32_e32 v31, v177
	v_readlane_b32 s73, v254, 36
	v_add_f32_dpp v27, v27, v27 row_half_mirror row_mask:0xf bank_mask:0xf bound_ctrl:1
	v_readlane_b32 s74, v254, 37
	v_readlane_b32 s75, v254, 38
	v_add_f32_dpp v27, v27, v27 row_mirror row_mask:0xf bank_mask:0xf bound_ctrl:1
	v_mov_b32_e32 v29, v27
	s_nop 1
	v_permlane16_swap_b32_e32 v27, v29
	v_add_f32_e32 v27, v27, v29
	v_mov_b32_e32 v29, v27
	s_nop 1
	v_permlane32_swap_b32_e32 v27, v29
	v_add_f32_e32 v27, v27, v29
	v_mul_f32_e32 v46, 0x3a800000, v27
	v_pk_add_f32 v[0:1], v[0:1], v[46:47] op_sel_hi:[1, 0] neg_lo:[0, 1] neg_hi:[0, 1]
	v_pk_add_f32 v[2:3], v[2:3], v[46:47] op_sel_hi:[1, 0] neg_lo:[0, 1] neg_hi:[0, 1]
	v_pk_add_f32 v[48:49], v[6:7], v[46:47] op_sel_hi:[1, 0] neg_lo:[0, 1] neg_hi:[0, 1]
	v_pk_mul_f32 v[6:7], v[0:1], v[0:1]
	v_pk_add_f32 v[50:51], v[4:5], v[46:47] op_sel_hi:[1, 0] neg_lo:[0, 1] neg_hi:[0, 1]
	v_pk_mul_f32 v[4:5], v[2:3], v[2:3]
	v_add_f32_e32 v6, v6, v7
	v_add_f32_e32 v4, v4, v6
	v_pk_mul_f32 v[52:53], v[50:51], v[50:51]
	v_add_f32_e32 v4, v5, v4
	v_add_f32_e32 v4, v52, v4
	v_pk_add_f32 v[10:11], v[10:11], v[46:47] op_sel_hi:[1, 0] neg_lo:[0, 1] neg_hi:[0, 1]
	v_pk_add_f32 v[8:9], v[8:9], v[46:47] op_sel_hi:[1, 0] neg_lo:[0, 1] neg_hi:[0, 1]
	v_pk_add_f32 v[14:15], v[14:15], v[46:47] op_sel_hi:[1, 0] neg_lo:[0, 1] neg_hi:[0, 1]
	v_pk_add_f32 v[12:13], v[12:13], v[46:47] op_sel_hi:[1, 0] neg_lo:[0, 1] neg_hi:[0, 1]
	v_pk_mul_f32 v[46:47], v[48:49], v[48:49]
	v_add_f32_e32 v4, v53, v4
	v_add_f32_e32 v4, v46, v4
	v_pk_mul_f32 v[56:57], v[8:9], v[8:9]
	v_add_f32_e32 v4, v47, v4
	v_add_f32_e32 v4, v56, v4
	v_pk_mul_f32 v[54:55], v[10:11], v[10:11]
	v_add_f32_e32 v4, v57, v4
	v_add_f32_e32 v4, v54, v4
	v_pk_mul_f32 v[60:61], v[12:13], v[12:13]
	v_add_f32_e32 v4, v55, v4
	v_add_f32_e32 v4, v60, v4
	v_pk_mul_f32 v[58:59], v[14:15], v[14:15]
	v_add_f32_e32 v4, v61, v4
	v_add_f32_e32 v4, v58, v4
	v_add_f32_e32 v4, v59, v4
	v_readlane_b32 s76, v254, 39
	v_readlane_b32 s77, v254, 40
	v_add_f32_dpp v4, v4, v4 quad_perm:[1, 0, 3, 2] row_mask:0xf bank_mask:0xf bound_ctrl:1
	v_readlane_b32 s78, v254, 41
	v_readlane_b32 s79, v254, 42
	v_add_f32_dpp v4, v4, v4 quad_perm:[2, 3, 0, 1] row_mask:0xf bank_mask:0xf bound_ctrl:1
	v_readlane_b32 s80, v254, 43
	v_readlane_b32 s81, v254, 44
	v_add_f32_dpp v4, v4, v4 row_half_mirror row_mask:0xf bank_mask:0xf bound_ctrl:1
	v_readlane_b32 s84, v254, 47
	s_waitcnt vmcnt(4)
	v_pk_add_f32 v[6:7], v[36:37], 1.0 op_sel_hi:[1, 0]
	v_add_f32_dpp v4, v4, v4 row_mirror row_mask:0xf bank_mask:0xf bound_ctrl:1
	v_mov_b32_e32 v5, v4
	s_nop 1
	v_permlane16_swap_b32_e32 v4, v5
	v_add_f32_e32 v27, v4, v5
	v_mov_b32_e32 v29, v27
	s_nop 1
	v_permlane32_swap_b32_e32 v27, v29
	v_add_f32_e32 v27, v27, v29
	v_fmamk_f32 v27, v27, 0x3a800000, v199
	v_mul_f32_e32 v29, 0x4b800000, v27
	v_cmp_gt_f32_e32 vcc, s0, v27
	v_pk_add_f32 v[4:5], v[34:35], 1.0 op_sel_hi:[1, 0]
	v_readlane_b32 s85, v254, 48
	v_cndmask_b32_e32 v27, v27, v29, vcc
	v_rsq_f32_e32 v29, v27
	v_mov_b32_e32 v27, v177
	v_lshl_add_u64 v[34:35], v[42:43], 0, v[26:27]
	v_readlane_b32 s86, v254, 49
	v_mul_f32_e32 v27, 0x45800000, v29
	v_cndmask_b32_e32 v36, v29, v27, vcc
	v_pk_mul_f32 v[0:1], v[0:1], v[36:37] op_sel_hi:[1, 0]
	v_pk_mul_f32 v[2:3], v[2:3], v[36:37] op_sel_hi:[1, 0]
	s_waitcnt vmcnt(3)
	v_pk_fma_f32 v[0:1], v[4:5], v[0:1], v[38:39]
	v_pk_fma_f32 v[2:3], v[6:7], v[2:3], v[40:41]
	v_cvt_pk_bf16_f32 v0, v0, v1
	v_cvt_pk_bf16_f32 v1, v2, v3
	global_store_dwordx2 v[32:33], v[0:1], off
	s_nop 0
	s_nop 0
	s_nop 0
	v_pk_mul_f32 v[38:39], v[50:51], v[36:37] op_sel_hi:[1, 0]
	v_pk_mul_f32 v[40:41], v[48:49], v[36:37] op_sel_hi:[1, 0]
	v_mov_b32_e32 v29, v177
	v_lshl_add_u64 v[34:35], v[42:43], 0, v[28:29]
	v_pk_mul_f32 v[8:9], v[8:9], v[36:37] op_sel_hi:[1, 0]
	v_pk_mul_f32 v[10:11], v[10:11], v[36:37] op_sel_hi:[1, 0]
	v_readlane_b32 s87, v254, 50
	s_waitcnt vmcnt(4)
	v_pk_add_f32 v[0:1], v[222:223], 1.0 op_sel_hi:[1, 0]
	v_pk_add_f32 v[2:3], v[224:225], 1.0 op_sel_hi:[1, 0]
	s_waitcnt vmcnt(3)
	v_pk_fma_f32 v[0:1], v[0:1], v[38:39], v[226:227]
	v_pk_fma_f32 v[2:3], v[2:3], v[40:41], v[228:229]
	v_cvt_pk_bf16_f32 v0, v0, v1
	v_cvt_pk_bf16_f32 v1, v2, v3
	global_store_dwordx2 v[32:33], v[0:1], off offset:512
	s_nop 0
	s_nop 0
	s_nop 0
	v_lshl_add_u64 v[34:35], v[42:43], 0, v[30:31]
	s_waitcnt vmcnt(4)
	v_pk_add_f32 v[0:1], v[230:231], 1.0 op_sel_hi:[1, 0]
	v_pk_add_f32 v[2:3], v[232:233], 1.0 op_sel_hi:[1, 0]
	s_waitcnt vmcnt(3)
	v_pk_fma_f32 v[0:1], v[0:1], v[8:9], v[234:235]
	v_pk_fma_f32 v[2:3], v[2:3], v[10:11], v[236:237]
	v_cvt_pk_bf16_f32 v0, v0, v1
	v_cvt_pk_bf16_f32 v1, v2, v3
	global_store_dwordx2 v[32:33], v[0:1], off offset:1024
	s_nop 0
	s_nop 0
	s_nop 0
	v_pk_mul_f32 v[8:9], v[12:13], v[36:37] op_sel_hi:[1, 0]
	v_pk_mul_f32 v[10:11], v[14:15], v[36:37] op_sel_hi:[1, 0]
	s_waitcnt vmcnt(4)
	v_pk_add_f32 v[0:1], v[238:239], 1.0 op_sel_hi:[1, 0]
	v_pk_add_f32 v[2:3], v[240:241], 1.0 op_sel_hi:[1, 0]
	s_waitcnt vmcnt(3)
	v_pk_fma_f32 v[0:1], v[8:9], v[0:1], v[242:243]
	v_pk_fma_f32 v[2:3], v[10:11], v[2:3], v[244:245]
	v_cvt_pk_bf16_f32 v0, v0, v1
	v_cvt_pk_bf16_f32 v1, v2, v3
	global_store_dwordx2 v[32:33], v[0:1], off offset:1536
	s_branch .LBB0_944
